# v34 + retention core heavy waves (query blocks 4-7) at s_setprio 1
# speedup vs baseline: 1.0042x; 1.0042x over previous
; __device__ __forceinline__ float log2_gamma(int hd) { const float e = ldexpf(1.0f, -5 - hd); float p = 1.0f / 7.0f; p = p * e + 1.0f / 6.0f; p = p * e + 0.2f; p = p * e + 0.25f; p = p * e + 1.0f / 3.0f; p = p * e + 0.5f; p = p * e + 1.0f; return -1.44269504089f * e * p; }
; __device__ __forceinline__ Frame relaunder(const Frame& F0) { Frame F = F0; int t = threadIdx.x; asm volatile("" : "+v"(t)); F.tid = t; F.lane = t & 63; F.wave = __builtin_amdgcn_readfirstlane(t >> 6); return F; }
; __device__ __forceinline__ void ret_core_phase(const Frame& F0, const bf16_t* hp, const bf16_t* qp, bf16_t* ro) {
;     const Frame F = relaunder(F0);
;     const int w = F.wave, lane = F.lane, l15 = lane & 15, g = lane >> 4, q = (lane & 15) >> 2, p = lane & 3;
;     const int lw = (w < 4) ? w : 11 - w;
;     const unsigned ldsb = (unsigned)(size_t)F.lds;
;     for (int item = F.vcu; item < 256; item += F.G) {
;         const int b = item >> 7, hd = (item >> 4) & 7, vs = item & 15;
;         const float l2g = log2_gamma(hd);
;         const float g128 = __builtin_amdgcn_exp2f(128.0f * l2g);
;         const bf16_t* qb = qp + ((size_t)((b * SEQ) >> 4) * 8 + hd) * 4096;
;         const bf16_t* kb = hp + (size_t)(b * SEQ) * RET_LD + D + hd * 256;
;         const bf16_t* vb = hp + (size_t)(b * SEQ) * RET_LD + 2 * D + hd * 512 + vs * 32;
;         bf16_t* ob = ro + (size_t)(b * SEQ) * 4096 + hd * 512 + vs * 32;
;         f32x4 T[2][2];
; #pragma unroll
;         for (int a = 0; a < 2; ++a)
; #pragma unroll
;             for (int c = 0; c < 2; ++c) T[a][c] = (f32x4){0.f, 0.f, 0.f, 0.f};
;         u32x4 kreg[8], vreg, qf[8];
;         const unsigned voffK = (unsigned)(F.tid >> 5) * (RET_LD * 2) + (unsigned)(F.tid & 31) * 16u, voffV = (unsigned)(F.tid >> 2) * (RET_LD * 2) + (unsigned)(F.tid & 3) * 16u;
;         const unsigned voffQ = (unsigned)lw * (8u * 8192u) + (unsigned)l15 * 64u + (unsigned)g * 16u;
;         constexpr size_t KSTEP = (size_t)16 * RET_LD * 2;
; #pragma unroll
;         for (int i = 0; i < 8; ++i) kreg[i] = *(const u32x4*)((const char*)kb + i * KSTEP + voffK);
;         vreg = *(const u32x4*)((const char*)vb + voffV);
; #pragma unroll
;         for (int ks = 0; ks < 8; ++ks) qf[ks] = *(const u32x4*)((const char*)qb + ks * 1024 + voffQ);
;         u32x2 ow[2];
;         const unsigned voffO = (unsigned)(16 * lw + l15) * 8192u + (unsigned)g * 8u;
.LBB0_772:
	v_readlane_b32 s4, v254, 47
	v_readlane_b32 s5, v254, 48
	s_andn2_b64 vcc, exec, s[4:5]
	s_cbranch_vccnz .LBB0_869
	v_readlane_b32 s8, v253, 45
	s_mov_b64 s[4:5], s[90:91]
	v_mov_b32_e32 v4, v0
	v_readlane_b32 s9, v253, 46
	s_andn2_b64 vcc, exec, s[8:9]
	v_readfirstlane_b32 s10, v4
	s_cbranch_vccnz .LBB0_827
	s_load_dwordx2 s[4:5], s[4:5], 0x98
	s_waitcnt vmcnt(0)
	v_lshlrev_b32_e32 v11, 4, v4
	v_and_b32_e32 v7, 15, v4
	v_ashrrev_i32_e32 v10, 5, v4
	v_and_b32_e32 v6, 0x1f0, v11
	s_waitcnt lgkmcnt(0)
	s_add_u32 s68, s4, 0xd000000
	s_addc_u32 s69, s5, 0
	s_add_u32 s70, s4, 0x5000000
	s_addc_u32 s71, s5, 0
	s_add_u32 s72, s4, 0x19400000
	s_addc_u32 s73, s5, 0
	s_ashr_i32 s4, s10, 6
	s_sub_i32 s5, 11, s4
	s_cmp_lt_i32 s4, 4
	s_movk_i32 s8, 0x6080
	s_cselect_b32 s34, s4, s5
	s_cmp_gt_i32 s34, 3
	s_cbranch_scc0 .Lmy_rcprio
	s_setprio 1
.Lmy_rcprio:
	v_mad_u64_u32 v[2:3], s[4:5], v10, s8, v[6:7]
	v_ashrrev_i32_e32 v12, 2, v4
	v_mul_lo_u32 v3, v12, s8
	v_and_b32_e32 v11, 48, v11
	v_bfe_u32 v9, v4, 4, 2
	v_or_b32_e32 v162, v3, v11
	s_lshl_b32 s4, s34, 16
	v_lshlrev_b32_e32 v3, 6, v7
	v_and_b32_e32 v13, 48, v4
	v_or3_b32 v164, s4, v3, v13
	s_lshl_b32 s4, s34, 17
	v_lshlrev_b32_e32 v14, 13, v7
	v_lshlrev_b32_e32 v15, 3, v9
	v_or3_b32 v166, s4, v14, v15
	s_movk_i32 s4, 0x50
	s_and_b32 s12, s10, 0xffffffc0
	v_readlane_b32 s14, v254, 20
	v_mul_lo_u32 v12, v12, s4
	s_add_i32 s4, s12, s14
	s_cmp_lt_i32 s34, 4
	v_bfe_u32 v8, v4, 2, 2
	v_add_u32_e32 v14, s4, v15
	s_cselect_b64 s[4:5], -1, 0
	s_cmp_gt_i32 s34, 3
	v_lshlrev_b32_e32 v9, 2, v9
	s_cselect_b64 s[8:9], -1, 0
	s_cmp_lt_u32 s10, 64
	v_or_b32_e32 v8, v9, v8
	v_lshlrev_b32_e32 v17, 3, v4
	s_cselect_b64 s[10:11], -1, 0
	v_mul_u32_u24_e32 v16, 0x50, v8
	v_and_b32_e32 v17, 24, v17
	v_mul_u32_u24_e32 v8, 0x210, v8
	s_add_i32 s12, s12, 0
	v_readlane_b32 s13, v254, 19
	v_add3_u32 v190, s12, v17, v8
	s_movk_i32 s12, 0x210
	v_and_b32_e32 v188, 63, v4
	v_add3_u32 v189, v17, s13, v16
	v_mul_lo_u32 v8, v10, s12
	v_add_u32_e32 v10, 0x200, v4
	v_add_u32_e32 v16, 0x400, v4
	v_add_u32_e32 v17, 0x600, v4
	v_add_u32_e32 v18, 0x800, v4
	v_add_u32_e32 v19, 0xa00, v4
	v_add_u32_e32 v20, 0xc00, v4
	v_add_u32_e32 v4, 0xe00, v4
	v_ashrrev_i32_e32 v10, 5, v10
	v_ashrrev_i32_e32 v16, 5, v16
	v_ashrrev_i32_e32 v17, 5, v17
	v_ashrrev_i32_e32 v18, 5, v18
	v_ashrrev_i32_e32 v19, 5, v19
	v_ashrrev_i32_e32 v20, 5, v20
	v_ashrrev_i32_e32 v4, 5, v4
	s_cmp_gt_i32 s34, -1
	v_add_u32_e32 v12, s13, v12
	v_mul_lo_u32 v10, v10, s12
	v_mul_lo_u32 v16, v16, s12
	v_mul_lo_u32 v17, v17, s12
	v_mul_lo_u32 v18, v18, s12
	v_mul_lo_u32 v19, v19, s12
	v_mul_lo_u32 v20, v20, s12
	v_mul_lo_u32 v4, v4, s12
	s_cselect_b64 s[12:13], -1, 0
	s_cmp_eq_u32 s34, 0
	v_add_u32_e32 v15, s14, v13
	s_cselect_b64 s[14:15], -1, 0
	s_cmp_gt_i32 s34, 0
	s_cselect_b64 s[16:17], -1, 0
	s_cmp_eq_u32 s34, 1
	s_cselect_b64 s[18:19], -1, 0
	s_cmp_gt_i32 s34, 1
	s_cselect_b64 s[20:21], -1, 0
	s_cmp_eq_u32 s34, 2
	s_cselect_b64 s[22:23], -1, 0
	s_cmp_gt_i32 s34, 2
	s_cselect_b64 s[24:25], -1, 0
	s_cmp_eq_u32 s34, 3
	s_cselect_b64 s[26:27], -1, 0
	s_cmp_eq_u32 s34, 4
	s_cselect_b64 s[28:29], -1, 0
	s_cmp_gt_i32 s34, 4
	s_cselect_b64 s[52:53], -1, 0
	s_cmp_eq_u32 s34, 5
	s_cselect_b64 s[54:55], -1, 0
	s_cmp_gt_i32 s34, 5
	s_cselect_b64 s[56:57], -1, 0
	s_cmp_eq_u32 s34, 6
	v_mul_u32_u24_e32 v21, 0x210, v7
	s_cselect_b64 s[58:59], -1, 0
	s_cmp_gt_i32 s34, 6
	v_add_u32_e32 v6, 0, v6
	v_lshlrev_b32_e32 v168, 7, v188
	v_add3_u32 v191, 0, v13, v21
	v_cmp_gt_u32_e64 s[38:39], v9, v7
	v_cmp_lt_u32_e64 s[40:41], v9, v7
	v_or_b32_e32 v13, 2, v9
	v_or_b32_e32 v9, 3, v9
	s_cselect_b64 s[60:61], -1, 0
	s_cmp_eq_u32 s34, 7
	v_mov_b32_e32 v3, v5
	v_mov_b32_e32 v163, v5
	v_mov_b32_e32 v165, v5
	v_mov_b32_e32 v167, v5
	v_mov_b32_e32 v169, v5
	v_and_b32_e32 v170, 0x180, v168
	v_mov_b32_e32 v171, v5
	v_cmp_gt_u32_e64 s[42:43], v13, v7
	v_cmp_gt_u32_e64 s[44:45], v9, v7
	s_cselect_b64 s[62:63], -1, 0
	v_add_u32_e32 v192, v6, v8
	v_add_u32_e32 v193, v6, v10
	v_add_u32_e32 v194, v6, v16
	v_add_u32_e32 v195, v6, v17
	v_add_u32_e32 v196, v6, v18
	v_add_u32_e32 v197, v6, v19
	v_add_u32_e32 v212, v6, v20
	v_add_u32_e32 v213, v6, v4
	v_add_u32_e32 v214, v12, v11
	v_add_u32_e32 v215, v14, v21
	v_add_u32_e32 v216, v15, v21
	v_readlane_b32 s74, v253, 0
	s_branch .LBB0_776

; #define PG8_STAGE(bufoff, gbase, voff) do { _Pragma("unroll") for (int _i = 0; _i < 2; ++_i) \
;         __builtin_amdgcn_global_load_lds((const unsigned*)((const char*)(gbase) + (voff)[_i]), (LAS unsigned*)(lds + (bufoff) + ldsw + _i * 8192), 16, 0, 0); } while (0)
; #define PG8_WAIT_V(n) asm volatile("s_waitcnt vmcnt(" #n ")" ::: "memory")
; #define PG8_BAR __builtin_amdgcn_s_barrier()
; template <class Epi, class Sched>
; __device__ __forceinline__ void gemm_phase(LAS unsigned char* lds, const Gemm g, const Sched& S, const Epi& E) {
;     ...
;     PG8_WAIT_V(2); PG8_BAR;
;     PG8_STAGE(PG8_SB(1, 0), cB + kstep, voffB); PG8_STAGE(PG8_SA(1, 0), cA + kstep, voffA); PG8_STAGE(PG8_SB(1, 1), cB + hstepB + kstep, voffB);
;     PG8_WAIT_V(6); PG8_BAR;
;     ...
; #pragma unroll
;         for (int a = 0; a < 2; ++a)
; #pragma unroll
;             for (int b = 0; b < 2; ++b)
; #pragma unroll
;                 for (int m = 0; m < 4; ++m)
; #pragma unroll
;                     for (int n = 0; n < 2; ++n) acc[a][b][m][n] = (f32x4){0.f, 0.f, 0.f, 0.f};
;         cur = nxt; cA = nA; cB = nB; ++ui;
.LBB0_995:
	v_mov_b32_e32 v139, v5
	v_lshl_add_u64 v[10:11], s[24:25], 0, v[138:139]
	v_mov_b32_e32 v135, v5
	v_lshl_add_u64 v[12:13], s[24:25], 0, v[134:135]
	v_mov_b32_e32 v141, v5
	s_add_i32 m0, s58, 0x18000
	v_lshl_add_u64 v[10:11], v[10:11], 0, s[36:37]
	v_lshl_add_u64 v[18:19], s[26:27], 0, v[140:141]
	v_mov_b32_e32 v137, v5
	s_waitcnt vmcnt(2)
	s_barrier
	global_load_lds_dwordx4 v[10:11], off
	v_lshl_add_u64 v[10:11], v[12:13], 0, s[36:37]
	s_add_i32 m0, s58, 0x1a000
	s_add_i32 s62, s58, 0x8000
	v_lshl_add_u64 v[20:21], s[26:27], 0, v[136:137]
	global_load_lds_dwordx4 v[10:11], off
	v_lshl_add_u64 v[10:11], v[18:19], 0, s[36:37]
	s_mov_b32 m0, s62
	s_add_i32 s63, s58, 0xa000
	v_lshl_add_u64 v[14:15], s[4:5], 0, v[138:139]
	global_load_lds_dwordx4 v[10:11], off
	v_lshl_add_u64 v[10:11], v[20:21], 0, s[36:37]
	s_mov_b32 m0, s63
	v_lshl_add_u64 v[16:17], s[4:5], 0, v[134:135]
	global_load_lds_dwordx4 v[10:11], off
	s_add_i32 m0, s58, 0x1c000
	v_lshl_add_u64 v[10:11], v[14:15], 0, s[36:37]
	global_load_lds_dwordx4 v[10:11], off
	v_lshl_add_u64 v[10:11], v[16:17], 0, s[36:37]
	s_add_i32 m0, s58, 0x1e000
	v_and_b32_e32 v168, 15, v169
	global_load_lds_dwordx4 v[10:11], off
	v_and_b32_e32 v9, 48, v169
	v_lshlrev_b32_e32 v10, 2, v169
	s_and_b32 s54, s50, 3
	s_lshr_b32 s64, s6, 6
	v_lshl_or_b32 v9, v168, 6, v9
	s_lshl_b32 s4, s52, 13
	v_and_b32_e32 v10, 32, v10
	v_bitop3_b32 v11, v9, s4, v10 bitop3:0xde
	s_lshl_b32 s4, s54, 12
	s_add_i32 s65, s64, -2
	s_cmpk_lt_u32 s51, 0x100
	v_bitop3_b32 v148, v9, s4, v10 bitop3:0xde
	s_cselect_b64 s[28:29], -1, 0
	s_add_u32 s4, s34, 0x80
	v_add_u32_e32 v4, v8, v4
	s_addc_u32 s5, 0, 0
	v_add_lshl_u32 v4, v4, v7, 1
	v_add_u32_e32 v2, v6, v2
	v_lshl_add_u64 v[142:143], s[4:5], 0, v[4:5]
	v_add_lshl_u32 v4, v2, v3, 1
	s_waitcnt vmcnt(6)
	v_lshl_add_u64 v[144:145], s[4:5], 0, v[4:5]
	v_mov_b32_e32 v4, v5
	v_mov_b32_e32 v2, v5
	v_mov_b32_e32 v3, v5
	v_add_u32_e32 v149, 0, v11
	v_mov_b64_e32 v[8:9], v[4:5]
	v_mov_b64_e32 v[12:13], v[4:5]
	v_mov_b64_e32 v[16:17], v[4:5]
	v_mov_b64_e32 v[20:21], v[4:5]
	v_mov_b64_e32 v[24:25], v[4:5]
	v_mov_b64_e32 v[32:33], v[4:5]
	v_mov_b64_e32 v[40:41], v[4:5]
	v_mov_b64_e32 v[48:49], v[4:5]
	v_mov_b64_e32 v[28:29], v[4:5]
	v_mov_b64_e32 v[36:37], v[4:5]
	v_mov_b64_e32 v[44:45], v[4:5]
	v_mov_b64_e32 v[52:53], v[4:5]
	v_mov_b64_e32 v[56:57], v[4:5]
	v_mov_b64_e32 v[60:61], v[4:5]
	v_mov_b64_e32 v[64:65], v[4:5]
	v_mov_b64_e32 v[68:69], v[4:5]
	v_mov_b64_e32 v[72:73], v[4:5]
	v_mov_b64_e32 v[76:77], v[4:5]
	v_mov_b64_e32 v[80:81], v[4:5]
	v_mov_b64_e32 v[84:85], v[4:5]
	v_mov_b64_e32 v[88:89], v[4:5]
	v_mov_b64_e32 v[96:97], v[4:5]
	v_mov_b64_e32 v[104:105], v[4:5]
	v_mov_b64_e32 v[116:117], v[4:5]
	v_mov_b64_e32 v[92:93], v[4:5]
	v_mov_b64_e32 v[100:101], v[4:5]
	v_mov_b64_e32 v[108:109], v[4:5]
	v_mov_b64_e32 v[112:113], v[4:5]
	v_mov_b64_e32 v[120:121], v[4:5]
	v_mov_b64_e32 v[124:125], v[4:5]
	v_mov_b64_e32 v[128:129], v[4:5]
	v_mov_b64_e32 v[132:133], v[4:5]
	v_readlane_b32 s4, v254, 13
	s_mov_b32 s66, 0
	v_mov_b64_e32 v[6:7], v[2:3]
	v_mov_b64_e32 v[10:11], v[2:3]
	v_mov_b64_e32 v[14:15], v[2:3]
	v_mov_b64_e32 v[18:19], v[2:3]
	v_mov_b64_e32 v[22:23], v[2:3]
	v_mov_b64_e32 v[30:31], v[2:3]
	v_mov_b64_e32 v[38:39], v[2:3]
	v_mov_b64_e32 v[46:47], v[2:3]
	v_mov_b64_e32 v[26:27], v[2:3]
	v_mov_b64_e32 v[34:35], v[2:3]
	v_mov_b64_e32 v[42:43], v[2:3]
	v_mov_b64_e32 v[50:51], v[2:3]
	v_mov_b64_e32 v[54:55], v[2:3]
	v_mov_b64_e32 v[58:59], v[2:3]
	v_mov_b64_e32 v[62:63], v[2:3]
	v_mov_b64_e32 v[66:67], v[2:3]
	v_mov_b64_e32 v[70:71], v[2:3]
	v_mov_b64_e32 v[74:75], v[2:3]
	v_mov_b64_e32 v[78:79], v[2:3]
	v_mov_b64_e32 v[82:83], v[2:3]
	v_mov_b64_e32 v[86:87], v[2:3]
	v_mov_b64_e32 v[94:95], v[2:3]
	v_mov_b64_e32 v[102:103], v[2:3]
	v_mov_b64_e32 v[114:115], v[2:3]
	v_mov_b64_e32 v[90:91], v[2:3]
	v_mov_b64_e32 v[98:99], v[2:3]
	v_mov_b64_e32 v[106:107], v[2:3]
	v_mov_b64_e32 v[110:111], v[2:3]
	v_mov_b64_e32 v[118:119], v[2:3]
	v_mov_b64_e32 v[122:123], v[2:3]
	v_mov_b64_e32 v[126:127], v[2:3]
	v_mov_b64_e32 v[130:131], v[2:3]
	s_mov_b32 s6, s4
	v_readlane_b32 s53, v253, 61
	s_barrier
	s_branch .LBB0_998
	s_nop 0
	s_nop 0
	s_nop 0
	s_nop 0
	s_nop 0
	s_nop 0
	s_nop 0
.LBB0_996:
	v_mov_b32_e32 v4, v5
	v_mov_b32_e32 v2, v5
	v_mov_b32_e32 v3, v5
	v_mov_b64_e32 v[8:9], v[4:5]
	v_mov_b64_e32 v[12:13], v[4:5]
	v_mov_b64_e32 v[16:17], v[4:5]
	v_mov_b64_e32 v[20:21], v[4:5]
	v_mov_b64_e32 v[24:25], v[4:5]
	v_mov_b64_e32 v[32:33], v[4:5]
	v_mov_b64_e32 v[40:41], v[4:5]
	v_mov_b64_e32 v[48:49], v[4:5]
	v_mov_b64_e32 v[28:29], v[4:5]
	v_mov_b64_e32 v[36:37], v[4:5]
	v_mov_b64_e32 v[44:45], v[4:5]
	v_mov_b64_e32 v[52:53], v[4:5]
	v_mov_b64_e32 v[56:57], v[4:5]
	v_mov_b64_e32 v[60:61], v[4:5]
	v_mov_b64_e32 v[64:65], v[4:5]
	v_mov_b64_e32 v[68:69], v[4:5]
	v_mov_b64_e32 v[72:73], v[4:5]
	v_mov_b64_e32 v[76:77], v[4:5]
	v_mov_b64_e32 v[80:81], v[4:5]
	v_mov_b64_e32 v[84:85], v[4:5]
	v_mov_b64_e32 v[88:89], v[4:5]
	v_mov_b64_e32 v[96:97], v[4:5]
	v_mov_b64_e32 v[104:105], v[4:5]
	v_mov_b64_e32 v[116:117], v[4:5]
	v_mov_b64_e32 v[92:93], v[4:5]
	v_mov_b64_e32 v[100:101], v[4:5]
	v_mov_b64_e32 v[108:109], v[4:5]
	v_mov_b64_e32 v[112:113], v[4:5]
	v_mov_b64_e32 v[120:121], v[4:5]
	v_mov_b64_e32 v[124:125], v[4:5]
	v_mov_b64_e32 v[128:129], v[4:5]
	v_mov_b64_e32 v[132:133], v[4:5]
	v_mov_b64_e32 v[6:7], v[2:3]
	v_mov_b64_e32 v[10:11], v[2:3]
	v_mov_b64_e32 v[14:15], v[2:3]
	v_mov_b64_e32 v[18:19], v[2:3]
	v_mov_b64_e32 v[22:23], v[2:3]
	v_mov_b64_e32 v[30:31], v[2:3]
	v_mov_b64_e32 v[38:39], v[2:3]
	v_mov_b64_e32 v[46:47], v[2:3]
	v_mov_b64_e32 v[26:27], v[2:3]
	v_mov_b64_e32 v[34:35], v[2:3]
	v_mov_b64_e32 v[42:43], v[2:3]
	v_mov_b64_e32 v[50:51], v[2:3]
	v_mov_b64_e32 v[54:55], v[2:3]
	v_mov_b64_e32 v[58:59], v[2:3]
	v_mov_b64_e32 v[62:63], v[2:3]
	v_mov_b64_e32 v[66:67], v[2:3]
	v_mov_b64_e32 v[70:71], v[2:3]
	v_mov_b64_e32 v[74:75], v[2:3]
	v_mov_b64_e32 v[78:79], v[2:3]
	v_mov_b64_e32 v[82:83], v[2:3]
	v_mov_b64_e32 v[86:87], v[2:3]
	v_mov_b64_e32 v[94:95], v[2:3]
	v_mov_b64_e32 v[102:103], v[2:3]
	v_mov_b64_e32 v[114:115], v[2:3]
	v_mov_b64_e32 v[90:91], v[2:3]
	v_mov_b64_e32 v[98:99], v[2:3]
	v_mov_b64_e32 v[106:107], v[2:3]
	v_mov_b64_e32 v[110:111], v[2:3]
	v_mov_b64_e32 v[118:119], v[2:3]
	v_mov_b64_e32 v[122:123], v[2:3]
	v_mov_b64_e32 v[126:127], v[2:3]
	v_mov_b64_e32 v[130:131], v[2:3]
	s_mov_b32 s6, s67
	s_mov_b32 s53, s68
	s_mov_b64 s[24:25], s[44:45]
	s_mov_b64 s[26:27], s[4:5]
	s_mov_b32 s66, s69
